# sample-group HGRN2 recurrence (all 512 units) moved to the computing workgroups' idle slot after the HGRN2 scan; streamers skip it
# baseline (speedup 1.0000x reference)
.LBB0_772:
	s_add_u32 s52, s72, 0x7400000
	s_addc_u32 s53, s73, 0
	s_add_u32 s70, s72, 0xa700000
	s_addc_u32 s71, s73, 0
	s_mov_b32 s100, 0x1234
	s_branch .LBB0_858
	s_nop 0
	s_nop 0
	s_nop 0
	s_nop 0
	s_nop 0
	s_nop 0
	s_nop 0
	s_nop 0
	s_nop 0
	s_nop 0
	s_nop 0
	s_nop 0
	s_nop 0
	s_nop 0
	s_nop 0
	s_nop 0
	s_nop 0
	s_nop 0
	s_nop 0
	s_nop 0
	s_nop 0
	s_nop 0
	s_nop 0
	s_nop 0
	s_nop 0
	s_nop 0
	s_nop 0
	s_nop 0
	s_nop 0
	s_nop 0
	s_nop 0
	s_nop 0
	s_nop 0
	s_nop 0
	s_nop 0
	s_nop 0
	s_nop 0
	s_nop 0
	s_nop 0
	s_nop 0
	s_nop 0
	s_nop 0
	s_nop 0
	s_nop 0
	s_nop 0
	s_nop 0
	s_nop 0
	s_nop 0
	s_nop 0
	s_nop 0
	s_nop 0
	s_nop 0
	s_nop 0
	s_nop 0
	s_nop 0

.LBB0_877:
	s_cmp_lg_u32 s100, 0x1234
	s_cbranch_scc1 .Lp5_cont
	s_mov_b32 s100, 0
	s_branch .Lp4_resume
	s_nop 0
	s_nop 0
	s_nop 0
	s_nop 0
	s_nop 0
	s_nop 0
	s_nop 0
	s_nop 0
	s_nop 0
	s_nop 0
	s_nop 0
	s_nop 0
	s_nop 0
	s_nop 0
	s_nop 0
	s_nop 0
	s_nop 0
	s_nop 0
	s_nop 0
	s_nop 0
	s_nop 0
	s_nop 0
	s_nop 0
	s_nop 0
	s_nop 0
	s_nop 0
	s_nop 0
	s_nop 0
	s_nop 0
	s_nop 0
	s_nop 0
	s_nop 0
	s_nop 0
	s_nop 0
	s_nop 0
	s_nop 0
	s_nop 0
	s_nop 0
	s_nop 0
	s_nop 0
	s_nop 0
	s_nop 0
	s_nop 0
	s_nop 0
	s_nop 0
	s_nop 0
	s_nop 0
	s_nop 0
	s_nop 0
	s_nop 0
	s_nop 0
	s_nop 0
	s_nop 0
	s_nop 0
	s_nop 0
	s_nop 0
	s_nop 0
	s_nop 0
	s_nop 0
	s_nop 0
	s_nop 0
